# all 2400 layer-1 weight conversion tiles moved into idle slots of the sample mixer phase
# baseline (speedup 1.0000x reference)
.LBB0_225:
	v_writelane_b32 v255, s12, 6
	s_andn2_b64 vcc, exec, s[4:5]
	s_nop 0
	v_writelane_b32 v255, s13, 7
	v_writelane_b32 v255, s0, 10
	s_nop 1
	v_writelane_b32 v255, s1, 11
	v_writelane_b32 v255, s77, 12
	s_cbranch_vccnz .LBB0_308
	s_cmp_eq_u32 s6, 14
	s_cselect_b32 vcc_lo, 1, 0
	v_writelane_b32 v255, vcc_lo, 30
	s_add_i32 s20, s6, 18
	s_cmp_gt_u32 s20, 38
	s_cselect_b64 s[0:1], -1, 0
	s_lshl_b32 s4, s74, 2
	v_writelane_b32 v255, s0, 4
	s_ashr_i32 s5, s4, 31
	s_lshl_b64 s[4:5], s[4:5], 2
	v_writelane_b32 v255, s1, 5
	v_readlane_b32 s0, v252, 24
	s_add_u32 s4, s0, s4
	v_readlane_b32 s0, v252, 25
	s_addc_u32 s5, s0, s5
	v_writelane_b32 v255, s4, 13
	s_cmp_lt_u32 s20, 39
	s_mov_b32 s0, 0x4c25000
	v_writelane_b32 v255, s5, 14
	s_movk_i32 s4, 0x600
	v_readlane_b32 s16, v255, 6
	v_readlane_b32 s17, v255, 7
	s_cselect_b32 s34, s4, 0x600
	s_and_b64 s[4:5], s[16:17], exec
	v_readlane_b32 s36, v252, 4
	s_cselect_b32 s4, s0, 0x9c25000
	v_readlane_b32 s50, v252, 18
	v_readlane_b32 s51, v252, 19
	s_add_u32 s0, s50, s4
	s_addc_u32 s1, s51, 0
	v_writelane_b32 v255, s0, 8
	s_and_b64 s[4:5], s[16:17], exec
	v_readlane_b32 s52, v253, 8
	v_writelane_b32 v255, s1, 9
	s_mov_b32 s0, 0xfd25000
	s_cselect_b32 s4, s0, 0x6425000
	s_add_u32 s0, s50, s4
	s_addc_u32 s1, s51, 0
	v_writelane_b32 v255, s0, 15
	v_readlane_b32 s66, v253, 22
	v_readlane_b32 s67, v253, 23
	v_writelane_b32 v255, s1, 16
	v_readlane_b32 s24, v252, 34
	v_readlane_b32 s0, v255, 2
	s_lshl_b32 s4, s0, 7
	s_ashr_i32 s5, s4, 31
	s_lshl_b64 s[4:5], s[4:5], 2
	v_readlane_b32 s1, v255, 3
	s_mov_b32 s26, s0
	s_add_u32 s0, s66, s4
	s_addc_u32 s1, s67, s5
	v_writelane_b32 v255, s0, 17
	s_and_b64 s[20:21], s[16:17], exec
	s_cselect_b32 s35, 4, 64
	v_writelane_b32 v255, s1, 18
	s_movk_i32 s0, 0x100
	s_cselect_b32 s13, s0, 0x1100
	s_cselect_b32 s14, 8, 12
	s_ashr_i32 s27, s26, 31
	s_lshl_b32 s0, s13, 8
	s_lshl_b32 s15, s13, 7
	s_lshr_b32 s77, s13, 6
	s_lshl_b32 s22, s13, 6
	s_lshl_b64 s[20:21], s[26:27], 2
	v_writelane_b32 v255, s0, 19
	v_readlane_b32 s25, v252, 35
	s_add_u32 s0, s24, s20
	v_cvt_f32_ubyte0_e32 v0, s35
	s_addc_u32 s1, s25, s21
	v_rcp_iflag_f32_e32 v0, v0
	s_add_u32 s20, s50, s20
	v_writelane_b32 v255, s0, 20
	s_addc_u32 s21, s51, s21
	v_readlane_b32 s38, v252, 6
	v_writelane_b32 v255, s1, 21
	s_add_u32 s0, s20, 0x4b24008
	s_addc_u32 s1, s21, 0
	v_mul_f32_e32 v0, 0x4f7ffffe, v0
	v_readlane_b32 s39, v252, 7
	s_add_u32 s28, s38, s4
	v_cvt_u32_f32_e32 v0, v0
	s_addc_u32 s29, s39, s5
	s_and_b64 s[4:5], s[16:17], exec
	s_cselect_b32 s16, 1, 16
	v_readfirstlane_b32 s5, v0
	v_cvt_f32_ubyte0_e32 v0, s16
	v_rcp_iflag_f32_e32 v0, v0
	v_writelane_b32 v255, s0, 22
	s_sub_i32 s4, 0, s35
	s_mul_i32 s4, s4, s5
	v_mul_f32_e32 v0, 0x4f7ffffe, v0
	v_cvt_u32_f32_e32 v0, v0
	v_writelane_b32 v255, s1, 23
	s_mov_b32 s0, s26
	v_writelane_b32 v255, s0, 2
	s_mul_hi_u32 s4, s5, s4
	s_mov_b32 s75, 0x60000
	v_writelane_b32 v255, s1, 3
	s_add_i32 s0, s5, s4
	s_sub_i32 s4, 0, s16
	v_readfirstlane_b32 s5, v0
	s_mul_i32 s4, s4, s5
	s_mul_hi_u32 s4, s5, s4
	s_mov_b32 s76, 0x8000
	s_mov_b32 s23, s95
	s_lshl_b32 s17, s26, 1
	v_writelane_b32 v255, s0, 24
	s_add_i32 s0, s5, s4
	s_sub_i32 s12, 0, s77
	s_mov_b32 s96, s71
	v_readlane_b32 s37, v252, 5
	v_readlane_b32 s40, v252, 8
	v_readlane_b32 s41, v252, 9
	v_readlane_b32 s42, v252, 10
	v_readlane_b32 s43, v252, 11
	v_readlane_b32 s44, v252, 12
	v_readlane_b32 s45, v252, 13
	v_readlane_b32 s46, v252, 14
	v_readlane_b32 s47, v252, 15
	v_readlane_b32 s48, v252, 16
	v_readlane_b32 s49, v252, 17
	v_readlane_b32 s53, v253, 9
	v_readlane_b32 s54, v253, 10
	v_readlane_b32 s55, v253, 11
	v_readlane_b32 s56, v253, 12
	v_readlane_b32 s57, v253, 13
	v_readlane_b32 s58, v253, 14
	v_readlane_b32 s59, v253, 15
	v_readlane_b32 s60, v253, 16
	v_readlane_b32 s61, v253, 17
	v_readlane_b32 s62, v253, 18
	v_readlane_b32 s63, v253, 19
	v_readlane_b32 s64, v253, 20
	v_readlane_b32 s65, v253, 21
	s_branch .LBB0_229

.Lattn_static:
	s_waitcnt lgkmcnt(0)
	ds_read_b32 v2, v196 offset:4
	v_readlane_b32 s99, v255, 12
	s_waitcnt lgkmcnt(0)
	v_readfirstlane_b32 s24, v2
	s_nop 3
	s_and_b32 s25, s99, 7
	s_lshl_b32 s25, s25, 6
	s_lshr_b32 s26, s99, 3
	s_or_b32 s25, s25, s26
	s_add_i32 s25, s25, 0x100
	s_cmpk_lt_u32 s99, 0x100
	s_cselect_b32 s26, 0, 1
	s_add_i32 s26, s26, s24
	s_add_i32 s24, s24, 1
	s_cmp_eq_u32 s26, 1
	s_cselect_b32 s98, s25, 0x300
	s_cmp_eq_u32 s26, 0
	s_cselect_b32 s98, s99, s98
	v_readlane_b32 vcc_hi, v255, 30
	s_nop 3
	s_cmpk_lt_u32 s99, 0x100
	s_cbranch_scc1 .Lcv_no
	s_cmp_eq_u32 vcc_hi, 0
	s_cbranch_scc1 .Lcv_no
	s_cmp_lt_u32 s26, 2
	s_cbranch_scc1 .Lcv_no
	s_cmp_gt_u32 s26, 11
	s_cbranch_scc1 .Lcv_no
	s_sub_u32 vcc_lo, s26, 2
	s_lshl_b32 vcc_lo, vcc_lo, 8
	s_add_u32 vcc_lo, s99, vcc_lo
	s_add_u32 vcc_lo, vcc_lo, 0x300
	s_cmpk_ge_u32 vcc_lo, 0xd60
	s_cbranch_scc1 .Lcv_no
	s_mov_b32 s98, vcc_lo
	s_branch .Lcv_keep
